# MLA: the 16 V^T transpose reads moved behind the last QK MFMA (fill the MFMA->VALU wait states, s_nop 10 dropped)
# baseline (speedup 1.0000x reference)
; #define MFMA32(a, b, c) __builtin_amdgcn_mfma_f32_32x32x16_bf16((a), (b), (c), 0, 0, 0)
; DI float pl32_max(float v) { auto rr = __builtin_amdgcn_permlane32_swap(__float_as_uint(v), __float_as_uint(v), false, false); return fmaxf(__uint_as_float(rr[0]), __uint_as_float(rr[1])); }
; template <int OFF> DI s16x4 tr_read_o(unsigned addr) { s16x4 r; asm volatile("ds_read_b64_tr_b16 %0, %1 offset:%2" : "=&v"(r) : "v"(addr), "i"(OFF) : "memory"); return r; }
; DI float max_nn(float a, float b) { return __builtin_amdgcn_fmed3f(a, b, __builtin_inff()); }
; DI void mla_unit(const Params& p, char* lds, int seqbase, int S, int h, int qb) {
;     ...
;     const u16* kl = Kl + cur * 64 * KP + r32 * KP + 8 * hi;
;     f32x16 p0, p1;
;     { const bf16x8 k0 = *(const bf16x8*)(kl), k1 = *(const bf16x8*)(kl + 32 * KP);
;       p0 = MFMA32(k0, qf[0], negm); p1 = MFMA32(k1, qf[0], negm); }
; #pragma unroll
;     for (int d0 = 1; d0 < 6; ++d0) {
;       const bf16x8 k0 = *(const bf16x8*)(kl + d0 * 16), k1 = *(const bf16x8*)(kl + 32 * KP + d0 * 16);
;       p0 = MFMA32(k0, qf[d0], p0); p1 = MFMA32(k1, qf[d0], p1);
;     }
;     const unsigned tb = trb + cur * (64 * VP * 2);
;     constexpr int R8 = 8 * VP * 2;
;     const s16x4 a0 = tr_read_o<0>(tb), b0 = tr_read_o<R8>(tb), a1 = tr_read_o<2 * R8>(tb), b1 = tr_read_o<3 * R8>(tb);
;     const s16x4 a2 = tr_read_o<4 * R8>(tb), b2 = tr_read_o<5 * R8>(tb), a3 = tr_read_o<6 * R8>(tb), b3 = tr_read_o<7 * R8>(tb);
;     const s16x4 c0 = tr_read_o<64>(tb), d0_ = tr_read_o<R8 + 64>(tb), c1 = tr_read_o<2 * R8 + 64>(tb), d1 = tr_read_o<3 * R8 + 64>(tb);
;     const s16x4 c2 = tr_read_o<4 * R8 + 64>(tb), d2 = tr_read_o<5 * R8 + 64>(tb), c3 = tr_read_o<6 * R8 + 64>(tb), d3 = tr_read_o<7 * R8 + 64>(tb);
;     float pmax = max_nn(p0[0], p1[0]);
; #pragma unroll
;     for (int r = 1; r < 16; ++r) pmax = max_nn(pmax, max_nn(p0[r], p1[r]));
;     pmax = pl32_max(pmax);
;     if (kt == 0 || __any(pmax > 8.f)) {
.LBB0_1081:
	s_mul_i32 s28, s36, 0x3400
	v_add_u32_e32 v0, s28, v181
	ds_read_b128 v[2:5], v0
	ds_read_b128 v[6:9], v0 offset:32
	s_mul_i32 s28, s36, 0x3000
	s_cmp_eq_u32 s46, 0
	s_cselect_b64 s[50:51], -1, 0
	s_waitcnt lgkmcnt(1)
	v_mfma_f32_32x32x16_bf16 v[64:79], v[2:5], v[116:119], v[48:63]
	ds_read_b128 v[2:5], v0 offset:6656
	ds_read_b128 v[10:13], v0 offset:6688
	s_cmp_lg_u32 s46, 0
	s_waitcnt lgkmcnt(1)
	v_mfma_f32_32x32x16_bf16 v[80:95], v[2:5], v[116:119], v[48:63]
	v_mfma_f32_32x32x16_bf16 v[64:79], v[6:9], v[120:123], v[64:79]
	ds_read_b128 v[2:5], v0 offset:64
	ds_read_b128 v[6:9], v0 offset:96
	s_waitcnt lgkmcnt(2)
	v_mfma_f32_32x32x16_bf16 v[80:95], v[10:13], v[120:123], v[80:95]
	s_waitcnt lgkmcnt(1)
	v_mfma_f32_32x32x16_bf16 v[64:79], v[2:5], v[124:127], v[64:79]
	ds_read_b128 v[2:5], v0 offset:6720
	ds_read_b128 v[10:13], v0 offset:6752
	s_waitcnt lgkmcnt(1)
	v_mfma_f32_32x32x16_bf16 v[80:95], v[2:5], v[124:127], v[80:95]
	ds_read_b128 v[2:5], v0 offset:128
	ds_read_b128 v[186:189], v0 offset:160
	v_mfma_f32_32x32x16_bf16 v[64:79], v[6:9], v[128:131], v[64:79]
	s_waitcnt lgkmcnt(2)
	v_mfma_f32_32x32x16_bf16 v[80:95], v[10:13], v[128:131], v[80:95]
	s_waitcnt lgkmcnt(1)
	v_mfma_f32_32x32x16_bf16 v[64:79], v[2:5], v[112:115], v[64:79]
	ds_read_b128 v[2:5], v0 offset:6784
	ds_read_b128 v[132:135], v0 offset:6816
	s_waitcnt lgkmcnt(1)
	v_mfma_f32_32x32x16_bf16 v[80:95], v[2:5], v[112:115], v[80:95]
	s_waitcnt lgkmcnt(0)
	v_mfma_f32_32x32x16_bf16 v[80:95], v[132:135], v[108:111], v[80:95]
	v_mfma_f32_32x32x16_bf16 v[64:79], v[186:189], v[108:111], v[64:79]
	v_add_u32_e32 v0, s28, v182
	ds_read_b64_tr_b16 v[144:145], v0 offset:0
	ds_read_b64_tr_b16 v[146:147], v0 offset:0x600
	ds_read_b64_tr_b16 v[136:137], v0 offset:0xc00
	ds_read_b64_tr_b16 v[138:139], v0 offset:0x1200
	ds_read_b64_tr_b16 v[10:11], v0 offset:0x1800
	ds_read_b64_tr_b16 v[12:13], v0 offset:0x1e00
	ds_read_b64_tr_b16 v[6:7], v0 offset:0x2400
	ds_read_b64_tr_b16 v[8:9], v0 offset:0x2a00
	ds_read_b64_tr_b16 v[148:149], v0 offset:64
	ds_read_b64_tr_b16 v[150:151], v0 offset:0x640
	ds_read_b64_tr_b16 v[140:141], v0 offset:0xc40
	ds_read_b64_tr_b16 v[142:143], v0 offset:0x1240
	ds_read_b64_tr_b16 v[132:133], v0 offset:0x1840
	ds_read_b64_tr_b16 v[134:135], v0 offset:0x1e40
	ds_read_b64_tr_b16 v[2:3], v0 offset:0x2440
	ds_read_b64_tr_b16 v[4:5], v0 offset:0x2a40
	v_max3_f32 v0, v80, v81, v82
	v_max3_f32 v14, v64, v65, v66
	v_max3_f32 v0, v0, v83, v84
	v_max3_f32 v14, v14, v67, v68
	v_max3_f32 v0, v0, v85, v86
	v_max3_f32 v14, v14, v69, v70
	v_max3_f32 v0, v0, v87, v88
	v_max3_f32 v14, v14, v71, v72
	v_max3_f32 v0, v0, v89, v90
	v_max3_f32 v14, v14, v73, v74
	v_max3_f32 v0, v0, v91, v92
	v_max3_f32 v14, v14, v75, v76
	v_max3_f32 v0, v0, v93, v94
	v_max3_f32 v14, v14, v77, v78
	v_max3_f32 v0, v0, v95, v79
	v_max_f32_e32 v14, v0, v14
	s_cbranch_scc0 .Lmla_k0_0
	v_cmp_lt_f32_e32 vcc, s60, v14
	s_mov_b64 s[54:55], 0
	s_mov_b64 s[52:53], 0
	s_cbranch_vccnz .Lmla_rare_0

; #define MFMA32(a, b, c) __builtin_amdgcn_mfma_f32_32x32x16_bf16((a), (b), (c), 0, 0, 0)
; DI float pl32_max(float v) { auto rr = __builtin_amdgcn_permlane32_swap(__float_as_uint(v), __float_as_uint(v), false, false); return fmaxf(__uint_as_float(rr[0]), __uint_as_float(rr[1])); }
; template <int OFF> DI s16x4 tr_read_o(unsigned addr) { s16x4 r; asm volatile("ds_read_b64_tr_b16 %0, %1 offset:%2" : "=&v"(r) : "v"(addr), "i"(OFF) : "memory"); return r; }
; DI float max_nn(float a, float b) { return __builtin_amdgcn_fmed3f(a, b, __builtin_inff()); }
; DI void mla_unit(const Params& p, char* lds, int seqbase, int S, int h, int qb) {
;     ...
;     const u16* kl = Kl + cur * 64 * KP + r32 * KP + 8 * hi;
;     f32x16 p0, p1;
;     { const bf16x8 k0 = *(const bf16x8*)(kl), k1 = *(const bf16x8*)(kl + 32 * KP);
;       p0 = MFMA32(k0, qf[0], negm); p1 = MFMA32(k1, qf[0], negm); }
; #pragma unroll
;     for (int d0 = 1; d0 < 6; ++d0) {
;       const bf16x8 k0 = *(const bf16x8*)(kl + d0 * 16), k1 = *(const bf16x8*)(kl + 32 * KP + d0 * 16);
;       p0 = MFMA32(k0, qf[d0], p0); p1 = MFMA32(k1, qf[d0], p1);
;     }
;     const unsigned tb = trb + cur * (64 * VP * 2);
;     constexpr int R8 = 8 * VP * 2;
;     const s16x4 a0 = tr_read_o<0>(tb), b0 = tr_read_o<R8>(tb), a1 = tr_read_o<2 * R8>(tb), b1 = tr_read_o<3 * R8>(tb);
;     const s16x4 a2 = tr_read_o<4 * R8>(tb), b2 = tr_read_o<5 * R8>(tb), a3 = tr_read_o<6 * R8>(tb), b3 = tr_read_o<7 * R8>(tb);
;     const s16x4 c0 = tr_read_o<64>(tb), d0_ = tr_read_o<R8 + 64>(tb), c1 = tr_read_o<2 * R8 + 64>(tb), d1 = tr_read_o<3 * R8 + 64>(tb);
;     const s16x4 c2 = tr_read_o<4 * R8 + 64>(tb), d2 = tr_read_o<5 * R8 + 64>(tb), c3 = tr_read_o<6 * R8 + 64>(tb), d3 = tr_read_o<7 * R8 + 64>(tb);
;     float pmax = max_nn(p0[0], p1[0]);
; #pragma unroll
;     for (int r = 1; r < 16; ++r) pmax = max_nn(pmax, max_nn(p0[r], p1[r]));
;     pmax = pl32_max(pmax);
;     if (kt == 0 || __any(pmax > 8.f)) {
.LBB0_1111:
	s_mul_i32 s28, s18, 0x3400
	v_add_u32_e32 v2, s28, v181
	ds_read_b128 v[4:7], v2
	ds_read_b128 v[8:11], v2 offset:32
	s_mul_i32 s28, s18, 0x3000
	s_cmp_eq_u32 s38, 0
	s_cselect_b64 s[46:47], -1, 0
	s_waitcnt lgkmcnt(1)
	v_mfma_f32_32x32x16_bf16 v[66:81], v[4:7], v[118:121], v[50:65]
	ds_read_b128 v[4:7], v2 offset:6656
	ds_read_b128 v[12:15], v2 offset:6688
	s_cmp_lg_u32 s38, 0
	s_waitcnt lgkmcnt(1)
	v_mfma_f32_32x32x16_bf16 v[82:97], v[4:7], v[118:121], v[50:65]
	v_mfma_f32_32x32x16_bf16 v[66:81], v[8:11], v[122:125], v[66:81]
	ds_read_b128 v[4:7], v2 offset:64
	ds_read_b128 v[8:11], v2 offset:96
	s_waitcnt lgkmcnt(2)
	v_mfma_f32_32x32x16_bf16 v[82:97], v[12:15], v[122:125], v[82:97]
	s_waitcnt lgkmcnt(1)
	v_mfma_f32_32x32x16_bf16 v[66:81], v[4:7], v[126:129], v[66:81]
	ds_read_b128 v[4:7], v2 offset:6720
	ds_read_b128 v[12:15], v2 offset:6752
	s_waitcnt lgkmcnt(1)
	v_mfma_f32_32x32x16_bf16 v[82:97], v[4:7], v[126:129], v[82:97]
	ds_read_b128 v[4:7], v2 offset:128
	ds_read_b128 v[188:191], v2 offset:160
	v_mfma_f32_32x32x16_bf16 v[66:81], v[8:11], v[130:133], v[66:81]
	s_waitcnt lgkmcnt(2)
	v_mfma_f32_32x32x16_bf16 v[82:97], v[12:15], v[130:133], v[82:97]
	s_waitcnt lgkmcnt(1)
	v_mfma_f32_32x32x16_bf16 v[66:81], v[4:7], v[114:117], v[66:81]
	ds_read_b128 v[4:7], v2 offset:6784
	ds_read_b128 v[134:137], v2 offset:6816
	s_waitcnt lgkmcnt(1)
	v_mfma_f32_32x32x16_bf16 v[82:97], v[4:7], v[114:117], v[82:97]
	s_waitcnt lgkmcnt(0)
	v_mfma_f32_32x32x16_bf16 v[82:97], v[134:137], v[110:113], v[82:97]
	v_mfma_f32_32x32x16_bf16 v[66:81], v[188:191], v[110:113], v[66:81]
	v_add_u32_e32 v2, s28, v182
	ds_read_b64_tr_b16 v[146:147], v2 offset:0
	ds_read_b64_tr_b16 v[148:149], v2 offset:0x600
	ds_read_b64_tr_b16 v[138:139], v2 offset:0xc00
	ds_read_b64_tr_b16 v[140:141], v2 offset:0x1200
	ds_read_b64_tr_b16 v[12:13], v2 offset:0x1800
	ds_read_b64_tr_b16 v[14:15], v2 offset:0x1e00
	ds_read_b64_tr_b16 v[8:9], v2 offset:0x2400
	ds_read_b64_tr_b16 v[10:11], v2 offset:0x2a00
	ds_read_b64_tr_b16 v[150:151], v2 offset:64
	ds_read_b64_tr_b16 v[152:153], v2 offset:0x640
	ds_read_b64_tr_b16 v[142:143], v2 offset:0xc40
	ds_read_b64_tr_b16 v[144:145], v2 offset:0x1240
	ds_read_b64_tr_b16 v[134:135], v2 offset:0x1840
	ds_read_b64_tr_b16 v[136:137], v2 offset:0x1e40
	ds_read_b64_tr_b16 v[4:5], v2 offset:0x2440
	ds_read_b64_tr_b16 v[6:7], v2 offset:0x2a40
	v_max3_f32 v2, v82, v83, v84
	v_max3_f32 v16, v66, v67, v68
	v_max3_f32 v2, v2, v85, v86
	v_max3_f32 v16, v16, v69, v70
	v_max3_f32 v2, v2, v87, v88
	v_max3_f32 v16, v16, v71, v72
	v_max3_f32 v2, v2, v89, v90
	v_max3_f32 v16, v16, v73, v74
	v_max3_f32 v2, v2, v91, v92
	v_max3_f32 v16, v16, v75, v76
	v_max3_f32 v2, v2, v93, v94
	v_max3_f32 v16, v16, v77, v78
	v_max3_f32 v2, v2, v95, v96
	v_max3_f32 v16, v16, v79, v80
	v_max3_f32 v2, v2, v97, v81
	v_max_f32_e32 v16, v2, v16
	s_cbranch_scc0 .Lmla_k0_1
	v_cmp_lt_f32_e32 vcc, s21, v16
	s_mov_b64 s[50:51], 0
	s_mov_b64 s[48:49], 0
	s_cbranch_vccnz .Lmla_rare_1
